# v22: v20 + top-k count loop: every second key counted via v_cmp to SGPR mask + s_bcnt1/s_add (SALU) instead of v_cmp+v_addc
# baseline (speedup 1.0000x reference)
; template <int NV>
; DI void topk_row(const float* row, int s, LAS int* lst, int lane) {
;     ...
; #pragma unroll 1
;     ...
;         const unsigned cand = T | (1u << bit); int c = 0;
; #pragma unroll
;         for (int j = 0; j < NV; ++j) asm volatile("v_cmp_le_u32 vcc, %2, %1\n\tv_addc_co_u32 %0, vcc, 0, %0, vcc" : "+v"(c) : "v"(key[j]), "s"(cand) : "vcc");
;         const int tot = wave_sum_i(c);
;         if (tot >= 256) T = cand;
;         if (tot == 256) break;
;     }
.LBB0_1969:
	s_mov_b32 s101, 0
	v_lshlrev_b32_e64 v54, v53, 1
	v_mov_b32_e32 v55, 0
	v_or_b32_e32 v54, v54, v34
	v_cmp_le_u32_e64 s[98:99], v54, v140
	v_cmp_le_u32 vcc, v54, v141
	v_addc_co_u32 v55, vcc, 0, v55, vcc
	s_bcnt1_i32_b64 s100, s[98:99]
	s_add_u32 s101, s101, s100
	v_cmp_le_u32_e64 s[98:99], v54, v138
	v_cmp_le_u32 vcc, v54, v139
	v_addc_co_u32 v55, vcc, 0, v55, vcc
	s_bcnt1_i32_b64 s100, s[98:99]
	s_add_u32 s101, s101, s100
	v_cmp_le_u32_e64 s[98:99], v54, v136
	v_cmp_le_u32 vcc, v54, v137
	v_addc_co_u32 v55, vcc, 0, v55, vcc
	s_bcnt1_i32_b64 s100, s[98:99]
	s_add_u32 s101, s101, s100
	v_cmp_le_u32_e64 s[98:99], v54, v134
	v_cmp_le_u32 vcc, v54, v135
	v_addc_co_u32 v55, vcc, 0, v55, vcc
	s_bcnt1_i32_b64 s100, s[98:99]
	s_add_u32 s101, s101, s100
	v_cmp_le_u32_e64 s[98:99], v54, v132
	v_cmp_le_u32 vcc, v54, v133
	v_addc_co_u32 v55, vcc, 0, v55, vcc
	s_bcnt1_i32_b64 s100, s[98:99]
	s_add_u32 s101, s101, s100
	v_cmp_le_u32_e64 s[98:99], v54, v248
	v_cmp_le_u32 vcc, v54, v251
	v_addc_co_u32 v55, vcc, 0, v55, vcc
	s_bcnt1_i32_b64 s100, s[98:99]
	s_add_u32 s101, s101, s100
	v_cmp_le_u32_e64 s[98:99], v54, v253
	v_cmp_le_u32 vcc, v54, v247
	v_addc_co_u32 v55, vcc, 0, v55, vcc
	s_bcnt1_i32_b64 s100, s[98:99]
	s_add_u32 s101, s101, s100
	v_cmp_le_u32_e64 s[98:99], v54, v252
	v_cmp_le_u32 vcc, v54, v249
	v_addc_co_u32 v55, vcc, 0, v55, vcc
	s_bcnt1_i32_b64 s100, s[98:99]
	s_add_u32 s101, s101, s100
	v_cmp_le_u32_e64 s[98:99], v54, v130
	v_cmp_le_u32 vcc, v54, v128
	v_addc_co_u32 v55, vcc, 0, v55, vcc
	s_bcnt1_i32_b64 s100, s[98:99]
	s_add_u32 s101, s101, s100
	v_cmp_le_u32_e64 s[98:99], v54, v129
	v_cmp_le_u32 vcc, v54, v131
	v_addc_co_u32 v55, vcc, 0, v55, vcc
	s_bcnt1_i32_b64 s100, s[98:99]
	s_add_u32 s101, s101, s100
	v_cmp_le_u32_e64 s[98:99], v54, v246
	v_cmp_le_u32 vcc, v54, v250
	v_addc_co_u32 v55, vcc, 0, v55, vcc
	s_bcnt1_i32_b64 s100, s[98:99]
	s_add_u32 s101, s101, s100
	v_cmp_le_u32_e64 s[98:99], v54, v244
	v_cmp_le_u32 vcc, v54, v245
	v_addc_co_u32 v55, vcc, 0, v55, vcc
	s_bcnt1_i32_b64 s100, s[98:99]
	s_add_u32 s101, s101, s100
	v_cmp_le_u32_e64 s[98:99], v54, v242
	v_cmp_le_u32 vcc, v54, v243
	v_addc_co_u32 v55, vcc, 0, v55, vcc
	s_bcnt1_i32_b64 s100, s[98:99]
	s_add_u32 s101, s101, s100
	v_cmp_le_u32_e64 s[98:99], v54, v240
	v_cmp_le_u32 vcc, v54, v241
	v_addc_co_u32 v55, vcc, 0, v55, vcc
	s_bcnt1_i32_b64 s100, s[98:99]
	s_add_u32 s101, s101, s100
	v_cmp_le_u32_e64 s[98:99], v54, v238
	v_cmp_le_u32 vcc, v54, v239
	v_addc_co_u32 v55, vcc, 0, v55, vcc
	s_bcnt1_i32_b64 s100, s[98:99]
	s_add_u32 s101, s101, s100
	v_cmp_le_u32_e64 s[98:99], v54, v236
	v_cmp_le_u32 vcc, v54, v237
	v_addc_co_u32 v55, vcc, 0, v55, vcc
	s_bcnt1_i32_b64 s100, s[98:99]
	s_add_u32 s101, s101, s100
	v_cmp_le_u32_e64 s[98:99], v54, v234
	v_cmp_le_u32 vcc, v54, v235
	v_addc_co_u32 v55, vcc, 0, v55, vcc
	s_bcnt1_i32_b64 s100, s[98:99]
	s_add_u32 s101, s101, s100
	v_cmp_le_u32_e64 s[98:99], v54, v232
	v_cmp_le_u32 vcc, v54, v233
	v_addc_co_u32 v55, vcc, 0, v55, vcc
	s_bcnt1_i32_b64 s100, s[98:99]
	s_add_u32 s101, s101, s100
	v_cmp_le_u32_e64 s[98:99], v54, v230
	v_cmp_le_u32 vcc, v54, v231
	v_addc_co_u32 v55, vcc, 0, v55, vcc
	s_bcnt1_i32_b64 s100, s[98:99]
	s_add_u32 s101, s101, s100
	v_cmp_le_u32_e64 s[98:99], v54, v228
	v_cmp_le_u32 vcc, v54, v229
	v_addc_co_u32 v55, vcc, 0, v55, vcc
	s_bcnt1_i32_b64 s100, s[98:99]
	s_add_u32 s101, s101, s100
	v_cmp_le_u32_e64 s[98:99], v54, v226
	v_cmp_le_u32 vcc, v54, v227
	v_addc_co_u32 v55, vcc, 0, v55, vcc
	s_bcnt1_i32_b64 s100, s[98:99]
	s_add_u32 s101, s101, s100
	v_cmp_le_u32_e64 s[98:99], v54, v224
	v_cmp_le_u32 vcc, v54, v225
	v_addc_co_u32 v55, vcc, 0, v55, vcc
	s_bcnt1_i32_b64 s100, s[98:99]
	s_add_u32 s101, s101, s100
	v_cmp_le_u32_e64 s[98:99], v54, v222
	v_cmp_le_u32 vcc, v54, v223
	v_addc_co_u32 v55, vcc, 0, v55, vcc
	s_bcnt1_i32_b64 s100, s[98:99]
	s_add_u32 s101, s101, s100
	v_cmp_le_u32_e64 s[98:99], v54, v220
	v_cmp_le_u32 vcc, v54, v221
	v_addc_co_u32 v55, vcc, 0, v55, vcc
	s_bcnt1_i32_b64 s100, s[98:99]
	s_add_u32 s101, s101, s100
	v_cmp_le_u32_e64 s[98:99], v54, v218
	v_cmp_le_u32 vcc, v54, v219
	v_addc_co_u32 v55, vcc, 0, v55, vcc
	s_bcnt1_i32_b64 s100, s[98:99]
	s_add_u32 s101, s101, s100
	v_cmp_le_u32_e64 s[98:99], v54, v216
	v_cmp_le_u32 vcc, v54, v217
	v_addc_co_u32 v55, vcc, 0, v55, vcc
	s_bcnt1_i32_b64 s100, s[98:99]
	s_add_u32 s101, s101, s100
	v_cmp_le_u32_e64 s[98:99], v54, v214
	v_cmp_le_u32 vcc, v54, v215
	v_addc_co_u32 v55, vcc, 0, v55, vcc
	s_bcnt1_i32_b64 s100, s[98:99]
	s_add_u32 s101, s101, s100
	v_cmp_le_u32_e64 s[98:99], v54, v212
	v_cmp_le_u32 vcc, v54, v213
	v_addc_co_u32 v55, vcc, 0, v55, vcc
	s_bcnt1_i32_b64 s100, s[98:99]
	s_add_u32 s101, s101, s100
	v_cmp_le_u32_e64 s[98:99], v54, v210
	v_cmp_le_u32 vcc, v54, v211
	v_addc_co_u32 v55, vcc, 0, v55, vcc
	s_bcnt1_i32_b64 s100, s[98:99]
	s_add_u32 s101, s101, s100
	v_cmp_le_u32_e64 s[98:99], v54, v208
	v_cmp_le_u32 vcc, v54, v209
	v_addc_co_u32 v55, vcc, 0, v55, vcc
	s_bcnt1_i32_b64 s100, s[98:99]
	s_add_u32 s101, s101, s100
	v_cmp_le_u32_e64 s[98:99], v54, v206
	v_cmp_le_u32 vcc, v54, v207
	v_addc_co_u32 v55, vcc, 0, v55, vcc
	s_bcnt1_i32_b64 s100, s[98:99]
	s_add_u32 s101, s101, s100
	v_cmp_le_u32_e64 s[98:99], v54, v204
	v_cmp_le_u32 vcc, v54, v205
	v_addc_co_u32 v55, vcc, 0, v55, vcc
	s_bcnt1_i32_b64 s100, s[98:99]
	s_add_u32 s101, s101, s100
	v_cmp_le_u32_e64 s[98:99], v54, v202
	v_cmp_le_u32 vcc, v54, v203
	v_addc_co_u32 v55, vcc, 0, v55, vcc
	s_bcnt1_i32_b64 s100, s[98:99]
	s_add_u32 s101, s101, s100
	v_cmp_le_u32_e64 s[98:99], v54, v200
	v_cmp_le_u32 vcc, v54, v201
	v_addc_co_u32 v55, vcc, 0, v55, vcc
; template <int NV>
; DI void topk_row(const float* row, int s, LAS int* lst, int lane) {
;     ...
; #pragma unroll 1
;     ...
;         const unsigned cand = T | (1u << bit); int c = 0;
; #pragma unroll
;         for (int j = 0; j < NV; ++j) asm volatile("v_cmp_le_u32 vcc, %2, %1\n\tv_addc_co_u32 %0, vcc, 0, %0, vcc" : "+v"(c) : "v"(key[j]), "s"(cand) : "vcc");
;         const int tot = wave_sum_i(c);
;         if (tot >= 256) T = cand;
;         if (tot == 256) break;
;     }
	s_bcnt1_i32_b64 s100, s[98:99]
	s_add_u32 s101, s101, s100
	v_cmp_le_u32_e64 s[98:99], v54, v198
	v_cmp_le_u32 vcc, v54, v199
	v_addc_co_u32 v55, vcc, 0, v55, vcc
	s_bcnt1_i32_b64 s100, s[98:99]
	s_add_u32 s101, s101, s100
	v_cmp_le_u32_e64 s[98:99], v54, v196
	v_cmp_le_u32 vcc, v54, v197
	v_addc_co_u32 v55, vcc, 0, v55, vcc
	s_bcnt1_i32_b64 s100, s[98:99]
	s_add_u32 s101, s101, s100
	v_cmp_le_u32_e64 s[98:99], v54, v194
	v_cmp_le_u32 vcc, v54, v195
	v_addc_co_u32 v55, vcc, 0, v55, vcc
	s_bcnt1_i32_b64 s100, s[98:99]
	s_add_u32 s101, s101, s100
	v_cmp_le_u32_e64 s[98:99], v54, v192
	v_cmp_le_u32 vcc, v54, v193
	v_addc_co_u32 v55, vcc, 0, v55, vcc
	s_bcnt1_i32_b64 s100, s[98:99]
	s_add_u32 s101, s101, s100
	v_cmp_le_u32_e64 s[98:99], v54, v190
	v_cmp_le_u32 vcc, v54, v191
	v_addc_co_u32 v55, vcc, 0, v55, vcc
	s_bcnt1_i32_b64 s100, s[98:99]
	s_add_u32 s101, s101, s100
	v_cmp_le_u32_e64 s[98:99], v54, v187
	v_cmp_le_u32 vcc, v54, v189
	v_addc_co_u32 v55, vcc, 0, v55, vcc
	s_bcnt1_i32_b64 s100, s[98:99]
	s_add_u32 s101, s101, s100
	v_cmp_le_u32_e64 s[98:99], v54, v186
	v_cmp_le_u32 vcc, v54, v188
	v_addc_co_u32 v55, vcc, 0, v55, vcc
	s_bcnt1_i32_b64 s100, s[98:99]
	s_add_u32 s101, s101, s100
	v_cmp_le_u32_e64 s[98:99], v54, v184
	v_cmp_le_u32 vcc, v54, v185
	v_addc_co_u32 v55, vcc, 0, v55, vcc
	s_bcnt1_i32_b64 s100, s[98:99]
	s_add_u32 s101, s101, s100
	v_cmp_le_u32_e64 s[98:99], v54, v182
	v_cmp_le_u32 vcc, v54, v183
	v_addc_co_u32 v55, vcc, 0, v55, vcc
	s_bcnt1_i32_b64 s100, s[98:99]
	s_add_u32 s101, s101, s100
	v_cmp_le_u32_e64 s[98:99], v54, v180
	v_cmp_le_u32 vcc, v54, v181
	v_addc_co_u32 v55, vcc, 0, v55, vcc
	s_bcnt1_i32_b64 s100, s[98:99]
	s_add_u32 s101, s101, s100
	v_cmp_le_u32_e64 s[98:99], v54, v178
	v_cmp_le_u32 vcc, v54, v179
	v_addc_co_u32 v55, vcc, 0, v55, vcc
	s_bcnt1_i32_b64 s100, s[98:99]
	s_add_u32 s101, s101, s100
	v_cmp_le_u32_e64 s[98:99], v54, v176
	v_cmp_le_u32 vcc, v54, v177
	v_addc_co_u32 v55, vcc, 0, v55, vcc
	s_bcnt1_i32_b64 s100, s[98:99]
	s_add_u32 s101, s101, s100
	v_cmp_le_u32_e64 s[98:99], v54, v174
	v_cmp_le_u32 vcc, v54, v175
	v_addc_co_u32 v55, vcc, 0, v55, vcc
	s_bcnt1_i32_b64 s100, s[98:99]
	s_add_u32 s101, s101, s100
	v_cmp_le_u32_e64 s[98:99], v54, v172
	v_cmp_le_u32 vcc, v54, v173
	v_addc_co_u32 v55, vcc, 0, v55, vcc
	s_bcnt1_i32_b64 s100, s[98:99]
	s_add_u32 s101, s101, s100
	v_cmp_le_u32_e64 s[98:99], v54, v170
	v_cmp_le_u32 vcc, v54, v171
	v_addc_co_u32 v55, vcc, 0, v55, vcc
	s_bcnt1_i32_b64 s100, s[98:99]
	s_add_u32 s101, s101, s100
	v_cmp_le_u32_e64 s[98:99], v54, v168
	v_cmp_le_u32 vcc, v54, v169
	v_addc_co_u32 v55, vcc, 0, v55, vcc
	s_bcnt1_i32_b64 s100, s[98:99]
	s_add_u32 s101, s101, s100
	v_cmp_le_u32_e64 s[98:99], v54, v164
	v_cmp_le_u32 vcc, v54, v166
	v_addc_co_u32 v55, vcc, 0, v55, vcc
	s_bcnt1_i32_b64 s100, s[98:99]
	s_add_u32 s101, s101, s100
	v_cmp_le_u32_e64 s[98:99], v54, v165
	v_cmp_le_u32 vcc, v54, v167
	v_addc_co_u32 v55, vcc, 0, v55, vcc
	s_bcnt1_i32_b64 s100, s[98:99]
	s_add_u32 s101, s101, s100
	v_cmp_le_u32_e64 s[98:99], v54, v163
	v_cmp_le_u32 vcc, v54, v162
	v_addc_co_u32 v55, vcc, 0, v55, vcc
	s_bcnt1_i32_b64 s100, s[98:99]
	s_add_u32 s101, s101, s100
	v_cmp_le_u32_e64 s[98:99], v54, v58
	v_cmp_le_u32 vcc, v54, v62
	v_addc_co_u32 v55, vcc, 0, v55, vcc
	s_bcnt1_i32_b64 s100, s[98:99]
	s_add_u32 s101, s101, s100
	v_cmp_le_u32_e64 s[98:99], v54, v52
	v_cmp_le_u32 vcc, v54, v56
	v_addc_co_u32 v55, vcc, 0, v55, vcc
	s_bcnt1_i32_b64 s100, s[98:99]
	s_add_u32 s101, s101, s100
	v_cmp_le_u32_e64 s[98:99], v54, v49
	v_cmp_le_u32 vcc, v54, v50
	v_addc_co_u32 v55, vcc, 0, v55, vcc
	s_bcnt1_i32_b64 s100, s[98:99]
	s_add_u32 s101, s101, s100
	v_cmp_le_u32_e64 s[98:99], v54, v51
	v_cmp_le_u32 vcc, v54, v48
	v_addc_co_u32 v55, vcc, 0, v55, vcc
	s_bcnt1_i32_b64 s100, s[98:99]
	s_add_u32 s101, s101, s100
	v_cmp_le_u32_e64 s[98:99], v54, v46
	v_cmp_le_u32 vcc, v54, v47
	v_addc_co_u32 v55, vcc, 0, v55, vcc
	s_bcnt1_i32_b64 s100, s[98:99]
	s_add_u32 s101, s101, s100
	v_cmp_le_u32_e64 s[98:99], v54, v44
	v_cmp_le_u32 vcc, v54, v45
	v_addc_co_u32 v55, vcc, 0, v55, vcc
	s_bcnt1_i32_b64 s100, s[98:99]
	s_add_u32 s101, s101, s100
	v_cmp_le_u32_e64 s[98:99], v54, v42
	v_cmp_le_u32 vcc, v54, v43
	v_addc_co_u32 v55, vcc, 0, v55, vcc
	s_bcnt1_i32_b64 s100, s[98:99]
	s_add_u32 s101, s101, s100
	v_cmp_le_u32_e64 s[98:99], v54, v40
	v_cmp_le_u32 vcc, v54, v41
	v_addc_co_u32 v55, vcc, 0, v55, vcc
	s_bcnt1_i32_b64 s100, s[98:99]
	s_add_u32 s101, s101, s100
	v_cmp_le_u32_e64 s[98:99], v54, v38
	v_cmp_le_u32 vcc, v54, v39
	v_addc_co_u32 v55, vcc, 0, v55, vcc
	s_bcnt1_i32_b64 s100, s[98:99]
	s_add_u32 s101, s101, s100
	v_cmp_le_u32_e64 s[98:99], v54, v36
	v_cmp_le_u32 vcc, v54, v37
	v_addc_co_u32 v55, vcc, 0, v55, vcc
	s_bcnt1_i32_b64 s100, s[98:99]
	s_add_u32 s101, s101, s100
	v_cmp_le_u32_e64 s[98:99], v54, v0
	v_cmp_le_u32 vcc, v54, v35
	v_addc_co_u32 v55, vcc, 0, v55, vcc
	s_bcnt1_i32_b64 s100, s[98:99]
	s_add_u32 s101, s101, s100
	s_nop 0
	s_nop 1
	v_add_u32_dpp v55, v55, v55 quad_perm:[1,0,3,2] row_mask:0xf bank_mask:0xf bound_ctrl:1
	s_nop 1
	v_add_u32_dpp v55, v55, v55 quad_perm:[2,3,0,1] row_mask:0xf bank_mask:0xf bound_ctrl:1
	s_nop 1
	v_add_u32_dpp v55, v55, v55 row_half_mirror row_mask:0xf bank_mask:0xf bound_ctrl:1
	s_nop 1
	v_add_u32_dpp v55, v55, v55 row_mirror row_mask:0xf bank_mask:0xf bound_ctrl:1
	s_nop 0
	v_readlane_b32 s0, v55, 0
	v_readlane_b32 s1, v55, 16
	s_add_i32 s0, s1, s0
	v_readlane_b32 s1, v55, 32
	s_add_i32 s0, s0, s1
	v_readlane_b32 s1, v55, 48
	s_add_i32 s0, s0, s1
	s_add_i32 s0, s0, s101
	s_cmpk_gt_i32 s0, 0xff
	s_cselect_b64 vcc, -1, 0
	s_cmpk_eq_i32 s0, 0x100
	v_cndmask_b32_e32 v34, v34, v54, vcc
	s_cselect_b64 s[0:1], -1, 0
	v_subrev_co_u32_e32 v53, vcc, 1, v53
	s_or_b64 s[0:1], s[0:1], vcc
	s_andn2_b64 vcc, exec, s[0:1]
	s_cbranch_vccnz .LBB0_1969
	v_cmp_gt_u32_e32 vcc, v141, v34
	s_and_saveexec_b64 s[0:1], vcc
	s_nop 0
	v_mbcnt_lo_u32_b32 v53, vcc_lo, 0
	v_mbcnt_hi_u32_b32 v53, vcc_hi, v53
	v_lshl_add_u32 v53, v53, 2, s20
	ds_write_b32 v53, v2
	s_or_b64 exec, exec, s[0:1]
	s_bcnt1_i32_b64 s2, vcc
	v_cmp_gt_u32_e32 vcc, v140, v34
	s_and_saveexec_b64 s[0:1], vcc
	s_cbranch_execz .LBB0_1974
	s_lshl_b32 s3, s2, 2
	v_mbcnt_lo_u32_b32 v53, vcc_lo, 0
	s_add_i32 s3, s20, s3
	v_mbcnt_hi_u32_b32 v53, vcc_hi, v53
	v_lshl_add_u32 v53, v53, 2, s3
	ds_write_b32 v53, v4

; template <int NV>
; DI void topk_row(const float* row, int s, LAS int* lst, int lane) {
;     ...
; #pragma unroll 1
;     ...
;         const unsigned cand = T | (1u << bit); int c = 0;
; #pragma unroll
;         for (int j = 0; j < NV; ++j) asm volatile("v_cmp_le_u32 vcc, %2, %1\n\tv_addc_co_u32 %0, vcc, 0, %0, vcc" : "+v"(c) : "v"(key[j]), "s"(cand) : "vcc");
;         const int tot = wave_sum_i(c);
;         if (tot >= 256) T = cand;
;         if (tot == 256) break;
;     }
.LBB0_2485:
	s_mov_b32 s101, 0
	v_lshlrev_b32_e64 v54, v53, 1
	v_mov_b32_e32 v55, 0
	v_or_b32_e32 v54, v54, v34
	v_cmp_le_u32_e64 s[98:99], v54, v220
	v_cmp_le_u32 vcc, v54, v221
	v_addc_co_u32 v55, vcc, 0, v55, vcc
	s_bcnt1_i32_b64 s100, s[98:99]
	s_add_u32 s101, s101, s100
	v_cmp_le_u32_e64 s[98:99], v54, v218
	v_cmp_le_u32 vcc, v54, v219
	v_addc_co_u32 v55, vcc, 0, v55, vcc
	s_bcnt1_i32_b64 s100, s[98:99]
	s_add_u32 s101, s101, s100
	v_cmp_le_u32_e64 s[98:99], v54, v216
	v_cmp_le_u32 vcc, v54, v217
	v_addc_co_u32 v55, vcc, 0, v55, vcc
	s_bcnt1_i32_b64 s100, s[98:99]
	s_add_u32 s101, s101, s100
	v_cmp_le_u32_e64 s[98:99], v54, v214
	v_cmp_le_u32 vcc, v54, v215
	v_addc_co_u32 v55, vcc, 0, v55, vcc
	s_bcnt1_i32_b64 s100, s[98:99]
	s_add_u32 s101, s101, s100
	v_cmp_le_u32_e64 s[98:99], v54, v211
	v_cmp_le_u32 vcc, v54, v213
	v_addc_co_u32 v55, vcc, 0, v55, vcc
	s_bcnt1_i32_b64 s100, s[98:99]
	s_add_u32 s101, s101, s100
	v_cmp_le_u32_e64 s[98:99], v54, v203
	v_cmp_le_u32 vcc, v54, v206
	v_addc_co_u32 v55, vcc, 0, v55, vcc
	s_bcnt1_i32_b64 s100, s[98:99]
	s_add_u32 s101, s101, s100
	v_cmp_le_u32_e64 s[98:99], v54, v202
	v_cmp_le_u32 vcc, v54, v200
	v_addc_co_u32 v55, vcc, 0, v55, vcc
	s_bcnt1_i32_b64 s100, s[98:99]
	s_add_u32 s101, s101, s100
	v_cmp_le_u32_e64 s[98:99], v54, v207
	v_cmp_le_u32 vcc, v54, v204
	v_addc_co_u32 v55, vcc, 0, v55, vcc
	s_bcnt1_i32_b64 s100, s[98:99]
	s_add_u32 s101, s101, s100
	v_cmp_le_u32_e64 s[98:99], v54, v212
	v_cmp_le_u32 vcc, v54, v208
	v_addc_co_u32 v55, vcc, 0, v55, vcc
	s_bcnt1_i32_b64 s100, s[98:99]
	s_add_u32 s101, s101, s100
	v_cmp_le_u32_e64 s[98:99], v54, v209
	v_cmp_le_u32 vcc, v54, v210
	v_addc_co_u32 v55, vcc, 0, v55, vcc
	s_bcnt1_i32_b64 s100, s[98:99]
	s_add_u32 s101, s101, s100
	v_cmp_le_u32_e64 s[98:99], v54, v201
	v_cmp_le_u32 vcc, v54, v205
	v_addc_co_u32 v55, vcc, 0, v55, vcc
	s_bcnt1_i32_b64 s100, s[98:99]
	s_add_u32 s101, s101, s100
	v_cmp_le_u32_e64 s[98:99], v54, v198
	v_cmp_le_u32 vcc, v54, v199
	v_addc_co_u32 v55, vcc, 0, v55, vcc
	s_bcnt1_i32_b64 s100, s[98:99]
	s_add_u32 s101, s101, s100
	v_cmp_le_u32_e64 s[98:99], v54, v196
	v_cmp_le_u32 vcc, v54, v197
	v_addc_co_u32 v55, vcc, 0, v55, vcc
	s_bcnt1_i32_b64 s100, s[98:99]
	s_add_u32 s101, s101, s100
	v_cmp_le_u32_e64 s[98:99], v54, v194
	v_cmp_le_u32 vcc, v54, v195
	v_addc_co_u32 v55, vcc, 0, v55, vcc
	s_bcnt1_i32_b64 s100, s[98:99]
	s_add_u32 s101, s101, s100
	v_cmp_le_u32_e64 s[98:99], v54, v192
	v_cmp_le_u32 vcc, v54, v193
	v_addc_co_u32 v55, vcc, 0, v55, vcc
	s_bcnt1_i32_b64 s100, s[98:99]
	s_add_u32 s101, s101, s100
	v_cmp_le_u32_e64 s[98:99], v54, v190
	v_cmp_le_u32 vcc, v54, v191
	v_addc_co_u32 v55, vcc, 0, v55, vcc
	s_bcnt1_i32_b64 s100, s[98:99]
	s_add_u32 s101, s101, s100
	v_cmp_le_u32_e64 s[98:99], v54, v188
	v_cmp_le_u32 vcc, v54, v189
	v_addc_co_u32 v55, vcc, 0, v55, vcc
	s_bcnt1_i32_b64 s100, s[98:99]
	s_add_u32 s101, s101, s100
	v_cmp_le_u32_e64 s[98:99], v54, v186
	v_cmp_le_u32 vcc, v54, v187
	v_addc_co_u32 v55, vcc, 0, v55, vcc
	s_bcnt1_i32_b64 s100, s[98:99]
	s_add_u32 s101, s101, s100
	v_cmp_le_u32_e64 s[98:99], v54, v184
	v_cmp_le_u32 vcc, v54, v185
	v_addc_co_u32 v55, vcc, 0, v55, vcc
	s_bcnt1_i32_b64 s100, s[98:99]
	s_add_u32 s101, s101, s100
	v_cmp_le_u32_e64 s[98:99], v54, v182
	v_cmp_le_u32 vcc, v54, v183
	v_addc_co_u32 v55, vcc, 0, v55, vcc
	s_bcnt1_i32_b64 s100, s[98:99]
	s_add_u32 s101, s101, s100
	v_cmp_le_u32_e64 s[98:99], v54, v180
	v_cmp_le_u32 vcc, v54, v181
	v_addc_co_u32 v55, vcc, 0, v55, vcc
	s_bcnt1_i32_b64 s100, s[98:99]
	s_add_u32 s101, s101, s100
	v_cmp_le_u32_e64 s[98:99], v54, v178
	v_cmp_le_u32 vcc, v54, v179
	v_addc_co_u32 v55, vcc, 0, v55, vcc
	s_bcnt1_i32_b64 s100, s[98:99]
	s_add_u32 s101, s101, s100
	v_cmp_le_u32_e64 s[98:99], v54, v176
	v_cmp_le_u32 vcc, v54, v177
	v_addc_co_u32 v55, vcc, 0, v55, vcc
	s_bcnt1_i32_b64 s100, s[98:99]
	s_add_u32 s101, s101, s100
	v_cmp_le_u32_e64 s[98:99], v54, v173
	v_cmp_le_u32 vcc, v54, v175
	v_addc_co_u32 v55, vcc, 0, v55, vcc
	s_bcnt1_i32_b64 s100, s[98:99]
	s_add_u32 s101, s101, s100
	v_cmp_le_u32_e64 s[98:99], v54, v172
	v_cmp_le_u32 vcc, v54, v174
	v_addc_co_u32 v55, vcc, 0, v55, vcc
	s_bcnt1_i32_b64 s100, s[98:99]
	s_add_u32 s101, s101, s100
	v_cmp_le_u32_e64 s[98:99], v54, v170
	v_cmp_le_u32 vcc, v54, v171
	v_addc_co_u32 v55, vcc, 0, v55, vcc
	s_bcnt1_i32_b64 s100, s[98:99]
	s_add_u32 s101, s101, s100
	v_cmp_le_u32_e64 s[98:99], v54, v168
	v_cmp_le_u32 vcc, v54, v169
	v_addc_co_u32 v55, vcc, 0, v55, vcc
	s_bcnt1_i32_b64 s100, s[98:99]
	s_add_u32 s101, s101, s100
	v_cmp_le_u32_e64 s[98:99], v54, v166
	v_cmp_le_u32 vcc, v54, v167
	v_addc_co_u32 v55, vcc, 0, v55, vcc
	s_bcnt1_i32_b64 s100, s[98:99]
; DI unsigned mbcnt64(unsigned long long m) { return __builtin_amdgcn_mbcnt_hi((unsigned)(m >> 32), __builtin_amdgcn_mbcnt_lo((unsigned)m, 0u)); }
; template <int NV>
; DI void topk_row(const float* row, int s, LAS int* lst, int lane) {
;     ...
; #pragma unroll 1
;     ...
;         const unsigned cand = T | (1u << bit); int c = 0;
; #pragma unroll
;         for (int j = 0; j < NV; ++j) asm volatile("v_cmp_le_u32 vcc, %2, %1\n\tv_addc_co_u32 %0, vcc, 0, %0, vcc" : "+v"(c) : "v"(key[j]), "s"(cand) : "vcc");
;         const int tot = wave_sum_i(c);
;         if (tot >= 256) T = cand;
;         if (tot == 256) break;
;     }
;     int bgt = 0;
; #pragma unroll
;     for (int j = 0; j < NV; ++j) { const bool sg = key[j] > T; const unsigned long long mg = __ballot(sg); if (sg) lst[bgt + (int)mbcnt64(mg)] = j * 64 + lane; bgt += __builtin_popcountll(mg); }
	s_add_u32 s101, s101, s100
	v_cmp_le_u32_e64 s[98:99], v54, v164
	v_cmp_le_u32 vcc, v54, v165
	v_addc_co_u32 v55, vcc, 0, v55, vcc
	s_bcnt1_i32_b64 s100, s[98:99]
	s_add_u32 s101, s101, s100
	v_cmp_le_u32_e64 s[98:99], v54, v162
	v_cmp_le_u32 vcc, v54, v163
	v_addc_co_u32 v55, vcc, 0, v55, vcc
	s_bcnt1_i32_b64 s100, s[98:99]
	s_add_u32 s101, s101, s100
	v_cmp_le_u32_e64 s[98:99], v54, v140
	v_cmp_le_u32 vcc, v54, v141
	v_addc_co_u32 v55, vcc, 0, v55, vcc
	s_bcnt1_i32_b64 s100, s[98:99]
	s_add_u32 s101, s101, s100
	v_cmp_le_u32_e64 s[98:99], v54, v138
	v_cmp_le_u32 vcc, v54, v139
	v_addc_co_u32 v55, vcc, 0, v55, vcc
	s_bcnt1_i32_b64 s100, s[98:99]
	s_add_u32 s101, s101, s100
	v_cmp_le_u32_e64 s[98:99], v54, v136
	v_cmp_le_u32 vcc, v54, v137
	v_addc_co_u32 v55, vcc, 0, v55, vcc
	s_bcnt1_i32_b64 s100, s[98:99]
	s_add_u32 s101, s101, s100
	v_cmp_le_u32_e64 s[98:99], v54, v134
	v_cmp_le_u32 vcc, v54, v135
	v_addc_co_u32 v55, vcc, 0, v55, vcc
	s_bcnt1_i32_b64 s100, s[98:99]
	s_add_u32 s101, s101, s100
	v_cmp_le_u32_e64 s[98:99], v54, v130
	v_cmp_le_u32 vcc, v54, v132
	v_addc_co_u32 v55, vcc, 0, v55, vcc
	s_bcnt1_i32_b64 s100, s[98:99]
	s_add_u32 s101, s101, s100
	v_cmp_le_u32_e64 s[98:99], v54, v131
	v_cmp_le_u32 vcc, v54, v133
	v_addc_co_u32 v55, vcc, 0, v55, vcc
	s_bcnt1_i32_b64 s100, s[98:99]
	s_add_u32 s101, s101, s100
	v_cmp_le_u32_e64 s[98:99], v54, v129
	v_cmp_le_u32 vcc, v54, v128
	v_addc_co_u32 v55, vcc, 0, v55, vcc
	s_bcnt1_i32_b64 s100, s[98:99]
	s_add_u32 s101, s101, s100
	v_cmp_le_u32_e64 s[98:99], v54, v58
	v_cmp_le_u32 vcc, v54, v62
	v_addc_co_u32 v55, vcc, 0, v55, vcc
	s_bcnt1_i32_b64 s100, s[98:99]
	s_add_u32 s101, s101, s100
	v_cmp_le_u32_e64 s[98:99], v54, v52
	v_cmp_le_u32 vcc, v54, v56
	v_addc_co_u32 v55, vcc, 0, v55, vcc
	s_bcnt1_i32_b64 s100, s[98:99]
	s_add_u32 s101, s101, s100
	v_cmp_le_u32_e64 s[98:99], v54, v49
	v_cmp_le_u32 vcc, v54, v50
	v_addc_co_u32 v55, vcc, 0, v55, vcc
	s_bcnt1_i32_b64 s100, s[98:99]
	s_add_u32 s101, s101, s100
	v_cmp_le_u32_e64 s[98:99], v54, v51
	v_cmp_le_u32 vcc, v54, v48
	v_addc_co_u32 v55, vcc, 0, v55, vcc
	s_bcnt1_i32_b64 s100, s[98:99]
	s_add_u32 s101, s101, s100
	v_cmp_le_u32_e64 s[98:99], v54, v46
	v_cmp_le_u32 vcc, v54, v47
	v_addc_co_u32 v55, vcc, 0, v55, vcc
	s_bcnt1_i32_b64 s100, s[98:99]
	s_add_u32 s101, s101, s100
	v_cmp_le_u32_e64 s[98:99], v54, v44
	v_cmp_le_u32 vcc, v54, v45
	v_addc_co_u32 v55, vcc, 0, v55, vcc
	s_bcnt1_i32_b64 s100, s[98:99]
	s_add_u32 s101, s101, s100
	v_cmp_le_u32_e64 s[98:99], v54, v42
	v_cmp_le_u32 vcc, v54, v43
	v_addc_co_u32 v55, vcc, 0, v55, vcc
	s_bcnt1_i32_b64 s100, s[98:99]
	s_add_u32 s101, s101, s100
	v_cmp_le_u32_e64 s[98:99], v54, v40
	v_cmp_le_u32 vcc, v54, v41
	v_addc_co_u32 v55, vcc, 0, v55, vcc
	s_bcnt1_i32_b64 s100, s[98:99]
	s_add_u32 s101, s101, s100
	v_cmp_le_u32_e64 s[98:99], v54, v38
	v_cmp_le_u32 vcc, v54, v39
	v_addc_co_u32 v55, vcc, 0, v55, vcc
	s_bcnt1_i32_b64 s100, s[98:99]
	s_add_u32 s101, s101, s100
	v_cmp_le_u32_e64 s[98:99], v54, v36
	v_cmp_le_u32 vcc, v54, v37
	v_addc_co_u32 v55, vcc, 0, v55, vcc
	s_bcnt1_i32_b64 s100, s[98:99]
	s_add_u32 s101, s101, s100
	v_cmp_le_u32_e64 s[98:99], v54, v0
	v_cmp_le_u32 vcc, v54, v35
	v_addc_co_u32 v55, vcc, 0, v55, vcc
	s_bcnt1_i32_b64 s100, s[98:99]
	s_add_u32 s101, s101, s100
	s_nop 0
	s_nop 1
	v_add_u32_dpp v55, v55, v55 quad_perm:[1,0,3,2] row_mask:0xf bank_mask:0xf bound_ctrl:1
	s_nop 1
	v_add_u32_dpp v55, v55, v55 quad_perm:[2,3,0,1] row_mask:0xf bank_mask:0xf bound_ctrl:1
	s_nop 1
	v_add_u32_dpp v55, v55, v55 row_half_mirror row_mask:0xf bank_mask:0xf bound_ctrl:1
	s_nop 1
	v_add_u32_dpp v55, v55, v55 row_mirror row_mask:0xf bank_mask:0xf bound_ctrl:1
	s_nop 0
	v_readlane_b32 s0, v55, 0
	v_readlane_b32 s1, v55, 16
	s_add_i32 s0, s1, s0
	v_readlane_b32 s1, v55, 32
	s_add_i32 s0, s0, s1
	v_readlane_b32 s1, v55, 48
	s_add_i32 s0, s0, s1
	s_add_i32 s0, s0, s101
	s_cmpk_gt_i32 s0, 0xff
	s_cselect_b64 vcc, -1, 0
	s_cmpk_eq_i32 s0, 0x100
	v_cndmask_b32_e32 v34, v34, v54, vcc
	s_cselect_b64 s[0:1], -1, 0
	v_subrev_co_u32_e32 v53, vcc, 1, v53
	s_or_b64 s[0:1], s[0:1], vcc
	s_andn2_b64 vcc, exec, s[0:1]
	s_cbranch_vccnz .LBB0_2485
	v_cmp_gt_u32_e32 vcc, v221, v34
	s_and_saveexec_b64 s[0:1], vcc
	s_nop 0
	v_mbcnt_lo_u32_b32 v53, vcc_lo, 0
	v_mbcnt_hi_u32_b32 v53, vcc_hi, v53
	v_lshl_add_u32 v53, v53, 2, s20
	ds_write_b32 v53, v2
	s_or_b64 exec, exec, s[0:1]
	s_bcnt1_i32_b64 s2, vcc
	v_cmp_gt_u32_e32 vcc, v220, v34
	s_and_saveexec_b64 s[0:1], vcc
	s_cbranch_execz .LBB0_2490
	s_lshl_b32 s3, s2, 2
	v_mbcnt_lo_u32_b32 v53, vcc_lo, 0
	s_add_i32 s3, s20, s3
	v_mbcnt_hi_u32_b32 v53, vcc_hi, v53
	v_lshl_add_u32 v53, v53, 2, s3
	ds_write_b32 v53, v4

; DI unsigned mbcnt64(unsigned long long m) { return __builtin_amdgcn_mbcnt_hi((unsigned)(m >> 32), __builtin_amdgcn_mbcnt_lo((unsigned)m, 0u)); }
; template <int NV>
; DI void topk_row(const float* row, int s, LAS int* lst, int lane) {
;     ...
; #pragma unroll 1
;     ...
;         const unsigned cand = T | (1u << bit); int c = 0;
; #pragma unroll
;         for (int j = 0; j < NV; ++j) asm volatile("v_cmp_le_u32 vcc, %2, %1\n\tv_addc_co_u32 %0, vcc, 0, %0, vcc" : "+v"(c) : "v"(key[j]), "s"(cand) : "vcc");
;         const int tot = wave_sum_i(c);
;         if (tot >= 256) T = cand;
;         if (tot == 256) break;
;     }
;     int bgt = 0;
; #pragma unroll
;     for (int j = 0; j < NV; ++j) { const bool sg = key[j] > T; const unsigned long long mg = __ballot(sg); if (sg) lst[bgt + (int)mbcnt64(mg)] = j * 64 + lane; bgt += __builtin_popcountll(mg); }
.LBB0_2871:
	s_mov_b32 s101, 0
	v_lshlrev_b32_e64 v54, v53, 1
	v_mov_b32_e32 v55, 0
	v_or_b32_e32 v54, v54, v34
	v_cmp_le_u32_e64 s[98:99], v54, v188
	v_cmp_le_u32 vcc, v54, v189
	v_addc_co_u32 v55, vcc, 0, v55, vcc
	s_bcnt1_i32_b64 s100, s[98:99]
	s_add_u32 s101, s101, s100
	v_cmp_le_u32_e64 s[98:99], v54, v186
	v_cmp_le_u32 vcc, v54, v187
	v_addc_co_u32 v55, vcc, 0, v55, vcc
	s_bcnt1_i32_b64 s100, s[98:99]
	s_add_u32 s101, s101, s100
	v_cmp_le_u32_e64 s[98:99], v54, v184
	v_cmp_le_u32 vcc, v54, v185
	v_addc_co_u32 v55, vcc, 0, v55, vcc
	s_bcnt1_i32_b64 s100, s[98:99]
	s_add_u32 s101, s101, s100
	v_cmp_le_u32_e64 s[98:99], v54, v182
	v_cmp_le_u32 vcc, v54, v183
	v_addc_co_u32 v55, vcc, 0, v55, vcc
	s_bcnt1_i32_b64 s100, s[98:99]
	s_add_u32 s101, s101, s100
	v_cmp_le_u32_e64 s[98:99], v54, v175
	v_cmp_le_u32 vcc, v54, v179
	v_addc_co_u32 v55, vcc, 0, v55, vcc
	s_bcnt1_i32_b64 s100, s[98:99]
	s_add_u32 s101, s101, s100
	v_cmp_le_u32_e64 s[98:99], v54, v170
	v_cmp_le_u32 vcc, v54, v172
	v_addc_co_u32 v55, vcc, 0, v55, vcc
	s_bcnt1_i32_b64 s100, s[98:99]
	s_add_u32 s101, s101, s100
	v_cmp_le_u32_e64 s[98:99], v54, v169
	v_cmp_le_u32 vcc, v54, v167
	v_addc_co_u32 v55, vcc, 0, v55, vcc
	s_bcnt1_i32_b64 s100, s[98:99]
	s_add_u32 s101, s101, s100
	v_cmp_le_u32_e64 s[98:99], v54, v178
	v_cmp_le_u32 vcc, v54, v174
	v_addc_co_u32 v55, vcc, 0, v55, vcc
	s_bcnt1_i32_b64 s100, s[98:99]
	s_add_u32 s101, s101, s100
	v_cmp_le_u32_e64 s[98:99], v54, v180
	v_cmp_le_u32 vcc, v54, v181
	v_addc_co_u32 v55, vcc, 0, v55, vcc
	s_bcnt1_i32_b64 s100, s[98:99]
	s_add_u32 s101, s101, s100
	v_cmp_le_u32_e64 s[98:99], v54, v176
	v_cmp_le_u32 vcc, v54, v177
	v_addc_co_u32 v55, vcc, 0, v55, vcc
	s_bcnt1_i32_b64 s100, s[98:99]
	s_add_u32 s101, s101, s100
	v_cmp_le_u32_e64 s[98:99], v54, v171
	v_cmp_le_u32 vcc, v54, v173
	v_addc_co_u32 v55, vcc, 0, v55, vcc
	s_bcnt1_i32_b64 s100, s[98:99]
	s_add_u32 s101, s101, s100
	v_cmp_le_u32_e64 s[98:99], v54, v166
	v_cmp_le_u32 vcc, v54, v168
	v_addc_co_u32 v55, vcc, 0, v55, vcc
	s_bcnt1_i32_b64 s100, s[98:99]
	s_add_u32 s101, s101, s100
	v_cmp_le_u32_e64 s[98:99], v54, v164
	v_cmp_le_u32 vcc, v54, v165
	v_addc_co_u32 v55, vcc, 0, v55, vcc
	s_bcnt1_i32_b64 s100, s[98:99]
	s_add_u32 s101, s101, s100
	v_cmp_le_u32_e64 s[98:99], v54, v162
	v_cmp_le_u32 vcc, v54, v163
	v_addc_co_u32 v55, vcc, 0, v55, vcc
	s_bcnt1_i32_b64 s100, s[98:99]
	s_add_u32 s101, s101, s100
	v_cmp_le_u32_e64 s[98:99], v54, v140
	v_cmp_le_u32 vcc, v54, v141
	v_addc_co_u32 v55, vcc, 0, v55, vcc
	s_bcnt1_i32_b64 s100, s[98:99]
	s_add_u32 s101, s101, s100
	v_cmp_le_u32_e64 s[98:99], v54, v138
	v_cmp_le_u32 vcc, v54, v139
	v_addc_co_u32 v55, vcc, 0, v55, vcc
	s_bcnt1_i32_b64 s100, s[98:99]
	s_add_u32 s101, s101, s100
	v_cmp_le_u32_e64 s[98:99], v54, v136
	v_cmp_le_u32 vcc, v54, v137
	v_addc_co_u32 v55, vcc, 0, v55, vcc
	s_bcnt1_i32_b64 s100, s[98:99]
	s_add_u32 s101, s101, s100
	v_cmp_le_u32_e64 s[98:99], v54, v134
	v_cmp_le_u32 vcc, v54, v135
	v_addc_co_u32 v55, vcc, 0, v55, vcc
	s_bcnt1_i32_b64 s100, s[98:99]
	s_add_u32 s101, s101, s100
	v_cmp_le_u32_e64 s[98:99], v54, v131
	v_cmp_le_u32 vcc, v54, v133
	v_addc_co_u32 v55, vcc, 0, v55, vcc
	s_bcnt1_i32_b64 s100, s[98:99]
	s_add_u32 s101, s101, s100
	v_cmp_le_u32_e64 s[98:99], v54, v130
	v_cmp_le_u32 vcc, v54, v132
	v_addc_co_u32 v55, vcc, 0, v55, vcc
	s_bcnt1_i32_b64 s100, s[98:99]
	s_add_u32 s101, s101, s100
	v_cmp_le_u32_e64 s[98:99], v54, v129
	v_cmp_le_u32 vcc, v54, v128
	v_addc_co_u32 v55, vcc, 0, v55, vcc
	s_bcnt1_i32_b64 s100, s[98:99]
	s_add_u32 s101, s101, s100
	v_cmp_le_u32_e64 s[98:99], v54, v58
	v_cmp_le_u32 vcc, v54, v62
	v_addc_co_u32 v55, vcc, 0, v55, vcc
	s_bcnt1_i32_b64 s100, s[98:99]
	s_add_u32 s101, s101, s100
	v_cmp_le_u32_e64 s[98:99], v54, v52
	v_cmp_le_u32 vcc, v54, v56
	v_addc_co_u32 v55, vcc, 0, v55, vcc
	s_bcnt1_i32_b64 s100, s[98:99]
	s_add_u32 s101, s101, s100
	v_cmp_le_u32_e64 s[98:99], v54, v49
	v_cmp_le_u32 vcc, v54, v50
	v_addc_co_u32 v55, vcc, 0, v55, vcc
	s_bcnt1_i32_b64 s100, s[98:99]
	s_add_u32 s101, s101, s100
	v_cmp_le_u32_e64 s[98:99], v54, v51
	v_cmp_le_u32 vcc, v54, v48
	v_addc_co_u32 v55, vcc, 0, v55, vcc
	s_bcnt1_i32_b64 s100, s[98:99]
	s_add_u32 s101, s101, s100
	v_cmp_le_u32_e64 s[98:99], v54, v46
	v_cmp_le_u32 vcc, v54, v47
	v_addc_co_u32 v55, vcc, 0, v55, vcc
	s_bcnt1_i32_b64 s100, s[98:99]
	s_add_u32 s101, s101, s100
	v_cmp_le_u32_e64 s[98:99], v54, v44
	v_cmp_le_u32 vcc, v54, v45
	v_addc_co_u32 v55, vcc, 0, v55, vcc
	s_bcnt1_i32_b64 s100, s[98:99]
	s_add_u32 s101, s101, s100
	v_cmp_le_u32_e64 s[98:99], v54, v42
	v_cmp_le_u32 vcc, v54, v43
	v_addc_co_u32 v55, vcc, 0, v55, vcc
	s_bcnt1_i32_b64 s100, s[98:99]
	s_add_u32 s101, s101, s100
	v_cmp_le_u32_e64 s[98:99], v54, v40
	v_cmp_le_u32 vcc, v54, v41
	v_addc_co_u32 v55, vcc, 0, v55, vcc
	s_bcnt1_i32_b64 s100, s[98:99]
	s_add_u32 s101, s101, s100
	v_cmp_le_u32_e64 s[98:99], v54, v38
	v_cmp_le_u32 vcc, v54, v39
	v_addc_co_u32 v55, vcc, 0, v55, vcc
	s_bcnt1_i32_b64 s100, s[98:99]
	s_add_u32 s101, s101, s100
	v_cmp_le_u32_e64 s[98:99], v54, v36
	v_cmp_le_u32 vcc, v54, v37
	v_addc_co_u32 v55, vcc, 0, v55, vcc
	s_bcnt1_i32_b64 s100, s[98:99]
	s_add_u32 s101, s101, s100
	v_cmp_le_u32_e64 s[98:99], v54, v0
	v_cmp_le_u32 vcc, v54, v35
	v_addc_co_u32 v55, vcc, 0, v55, vcc
	s_bcnt1_i32_b64 s100, s[98:99]
	s_add_u32 s101, s101, s100
	s_nop 0
	s_nop 1
	v_add_u32_dpp v55, v55, v55 quad_perm:[1,0,3,2] row_mask:0xf bank_mask:0xf bound_ctrl:1
	s_nop 1
	v_add_u32_dpp v55, v55, v55 quad_perm:[2,3,0,1] row_mask:0xf bank_mask:0xf bound_ctrl:1
	s_nop 1
	v_add_u32_dpp v55, v55, v55 row_half_mirror row_mask:0xf bank_mask:0xf bound_ctrl:1
	s_nop 1
	v_add_u32_dpp v55, v55, v55 row_mirror row_mask:0xf bank_mask:0xf bound_ctrl:1
	s_nop 0
	v_readlane_b32 s0, v55, 0
	v_readlane_b32 s1, v55, 16
	s_add_i32 s0, s1, s0
	v_readlane_b32 s1, v55, 32
	s_add_i32 s0, s0, s1
	v_readlane_b32 s1, v55, 48
	s_add_i32 s0, s0, s1
	s_add_i32 s0, s0, s101
	s_cmpk_gt_i32 s0, 0xff
	s_cselect_b64 vcc, -1, 0
	s_cmpk_eq_i32 s0, 0x100
	v_cndmask_b32_e32 v34, v34, v54, vcc
	s_cselect_b64 s[0:1], -1, 0
	v_subrev_co_u32_e32 v53, vcc, 1, v53
	s_or_b64 s[0:1], s[0:1], vcc
	s_andn2_b64 vcc, exec, s[0:1]
	s_cbranch_vccnz .LBB0_2871
	v_cmp_gt_u32_e32 vcc, v189, v34
	s_and_saveexec_b64 s[0:1], vcc
	s_nop 0
	v_mbcnt_lo_u32_b32 v53, vcc_lo, 0
	v_mbcnt_hi_u32_b32 v53, vcc_hi, v53
	v_lshl_add_u32 v53, v53, 2, s20
	ds_write_b32 v53, v2
	s_or_b64 exec, exec, s[0:1]
	s_bcnt1_i32_b64 s2, vcc
	v_cmp_gt_u32_e32 vcc, v188, v34
	s_and_saveexec_b64 s[0:1], vcc
	s_cbranch_execz .LBB0_2876
	s_lshl_b32 s3, s2, 2
	v_mbcnt_lo_u32_b32 v53, vcc_lo, 0
	s_add_i32 s3, s20, s3
	v_mbcnt_hi_u32_b32 v53, vcc_hi, v53
	v_lshl_add_u32 v53, v53, 2, s3
	ds_write_b32 v53, v4

; DI unsigned mbcnt64(unsigned long long m) { return __builtin_amdgcn_mbcnt_hi((unsigned)(m >> 32), __builtin_amdgcn_mbcnt_lo((unsigned)m, 0u)); }
; DI int wave_sum_i(int v) {
;     v += __builtin_amdgcn_update_dpp(0, v, 0xB1, 0xF, 0xF, true);
;     v += __builtin_amdgcn_update_dpp(0, v, 0x4E, 0xF, 0xF, true);
;     v += __builtin_amdgcn_update_dpp(0, v, 0x141, 0xF, 0xF, true);
;     v += __builtin_amdgcn_update_dpp(0, v, 0x140, 0xF, 0xF, true);
;     return __builtin_amdgcn_readlane(v, 0) + __builtin_amdgcn_readlane(v, 16) + __builtin_amdgcn_readlane(v, 32) + __builtin_amdgcn_readlane(v, 48);
; template <int NV>
; DI void topk_row(const float* row, int s, LAS int* lst, int lane) {
;     ...
;         const unsigned cand = T | (1u << bit); int c = 0;
; #pragma unroll
;         for (int j = 0; j < NV; ++j) asm volatile("v_cmp_le_u32 vcc, %2, %1\n\tv_addc_co_u32 %0, vcc, 0, %0, vcc" : "+v"(c) : "v"(key[j]), "s"(cand) : "vcc");
;         const int tot = wave_sum_i(c);
;         if (tot >= 256) T = cand;
;         if (tot == 256) break;
;     }
;     int bgt = 0;
; #pragma unroll
;     for (int j = 0; j < NV; ++j) { const bool sg = key[j] > T; const unsigned long long mg = __ballot(sg); if (sg) lst[bgt + (int)mbcnt64(mg)] = j * 64 + lane; bgt += __builtin_popcountll(mg); }
.LBB0_3129:
	s_mov_b32 s101, 0
	v_lshlrev_b32_e64 v131, v130, 1
	v_mov_b32_e32 v132, 0
	v_or_b32_e32 v131, v131, v129
	v_cmp_le_u32_e64 s[98:99], v131, v43
	v_cmp_le_u32 vcc, v131, v44
	v_addc_co_u32 v132, vcc, 0, v132, vcc
	s_bcnt1_i32_b64 s100, s[98:99]
	s_add_u32 s101, s101, s100
	v_cmp_le_u32_e64 s[98:99], v131, v41
	v_cmp_le_u32 vcc, v131, v42
	v_addc_co_u32 v132, vcc, 0, v132, vcc
	s_bcnt1_i32_b64 s100, s[98:99]
	s_add_u32 s101, s101, s100
	v_cmp_le_u32_e64 s[98:99], v131, v39
	v_cmp_le_u32 vcc, v131, v40
	v_addc_co_u32 v132, vcc, 0, v132, vcc
	s_bcnt1_i32_b64 s100, s[98:99]
	s_add_u32 s101, s101, s100
	v_cmp_le_u32_e64 s[98:99], v131, v37
	v_cmp_le_u32 vcc, v131, v38
	v_addc_co_u32 v132, vcc, 0, v132, vcc
	s_bcnt1_i32_b64 s100, s[98:99]
	s_add_u32 s101, s101, s100
	v_cmp_le_u32_e64 s[98:99], v131, v35
	v_cmp_le_u32 vcc, v131, v36
	v_addc_co_u32 v132, vcc, 0, v132, vcc
	s_bcnt1_i32_b64 s100, s[98:99]
	s_add_u32 s101, s101, s100
	v_cmp_le_u32_e64 s[98:99], v131, v45
	v_cmp_le_u32 vcc, v131, v34
	v_addc_co_u32 v132, vcc, 0, v132, vcc
	s_bcnt1_i32_b64 s100, s[98:99]
	s_add_u32 s101, s101, s100
	v_cmp_le_u32_e64 s[98:99], v131, v47
	v_cmp_le_u32 vcc, v131, v46
	v_addc_co_u32 v132, vcc, 0, v132, vcc
	s_bcnt1_i32_b64 s100, s[98:99]
	s_add_u32 s101, s101, s100
	v_cmp_le_u32_e64 s[98:99], v131, v51
	v_cmp_le_u32 vcc, v131, v48
	v_addc_co_u32 v132, vcc, 0, v132, vcc
	s_bcnt1_i32_b64 s100, s[98:99]
	s_add_u32 s101, s101, s100
	v_cmp_le_u32_e64 s[98:99], v131, v63
	v_cmp_le_u32 vcc, v131, v57
	v_addc_co_u32 v132, vcc, 0, v132, vcc
	s_bcnt1_i32_b64 s100, s[98:99]
	s_add_u32 s101, s101, s100
	v_cmp_le_u32_e64 s[98:99], v131, v61
	v_cmp_le_u32 vcc, v131, v62
	v_addc_co_u32 v132, vcc, 0, v132, vcc
	s_bcnt1_i32_b64 s100, s[98:99]
	s_add_u32 s101, s101, s100
	v_cmp_le_u32_e64 s[98:99], v131, v59
	v_cmp_le_u32 vcc, v131, v60
	v_addc_co_u32 v132, vcc, 0, v132, vcc
	s_bcnt1_i32_b64 s100, s[98:99]
	s_add_u32 s101, s101, s100
	v_cmp_le_u32_e64 s[98:99], v131, v56
	v_cmp_le_u32 vcc, v131, v58
	v_addc_co_u32 v132, vcc, 0, v132, vcc
	s_bcnt1_i32_b64 s100, s[98:99]
	s_add_u32 s101, s101, s100
	v_cmp_le_u32_e64 s[98:99], v131, v54
	v_cmp_le_u32 vcc, v131, v55
	v_addc_co_u32 v132, vcc, 0, v132, vcc
	s_bcnt1_i32_b64 s100, s[98:99]
	s_add_u32 s101, s101, s100
	v_cmp_le_u32_e64 s[98:99], v131, v52
	v_cmp_le_u32 vcc, v131, v53
	v_addc_co_u32 v132, vcc, 0, v132, vcc
	s_bcnt1_i32_b64 s100, s[98:99]
	s_add_u32 s101, s101, s100
	v_cmp_le_u32_e64 s[98:99], v131, v49
	v_cmp_le_u32 vcc, v131, v50
	v_addc_co_u32 v132, vcc, 0, v132, vcc
	s_bcnt1_i32_b64 s100, s[98:99]
	s_add_u32 s101, s101, s100
	v_cmp_le_u32_e64 s[98:99], v131, v128
	v_cmp_le_u32 vcc, v131, v0
	v_addc_co_u32 v132, vcc, 0, v132, vcc
	s_bcnt1_i32_b64 s100, s[98:99]
	s_add_u32 s101, s101, s100
	s_nop 0
	s_nop 1
	v_add_u32_dpp v132, v132, v132 quad_perm:[1,0,3,2] row_mask:0xf bank_mask:0xf bound_ctrl:1
	s_nop 1
	v_add_u32_dpp v132, v132, v132 quad_perm:[2,3,0,1] row_mask:0xf bank_mask:0xf bound_ctrl:1
	s_nop 1
	v_add_u32_dpp v132, v132, v132 row_half_mirror row_mask:0xf bank_mask:0xf bound_ctrl:1
	s_nop 1
	v_add_u32_dpp v132, v132, v132 row_mirror row_mask:0xf bank_mask:0xf bound_ctrl:1
	s_nop 0
	v_readlane_b32 s0, v132, 0
	v_readlane_b32 s1, v132, 16
	s_add_i32 s0, s1, s0
	v_readlane_b32 s1, v132, 32
	s_add_i32 s0, s0, s1
	v_readlane_b32 s1, v132, 48
	s_add_i32 s0, s0, s1
	s_add_i32 s0, s0, s101
	s_cmpk_gt_i32 s0, 0xff
	s_cselect_b64 vcc, -1, 0
	s_cmpk_eq_i32 s0, 0x100
	v_cndmask_b32_e32 v129, v129, v131, vcc
	s_cselect_b64 s[0:1], -1, 0
	v_subrev_co_u32_e32 v130, vcc, 1, v130
	s_or_b64 s[0:1], s[0:1], vcc
	s_andn2_b64 vcc, exec, s[0:1]
	s_cbranch_vccnz .LBB0_3129
	v_cmp_gt_u32_e32 vcc, v44, v129
	s_and_saveexec_b64 s[0:1], vcc
	s_nop 0
	v_mbcnt_lo_u32_b32 v130, vcc_lo, 0
	v_mbcnt_hi_u32_b32 v130, vcc_hi, v130
	v_lshl_add_u32 v130, v130, 2, s20
	ds_write_b32 v130, v2
	s_or_b64 exec, exec, s[0:1]
	s_bcnt1_i32_b64 s2, vcc
	v_cmp_gt_u32_e32 vcc, v43, v129
	s_and_saveexec_b64 s[0:1], vcc
	s_cbranch_execz .LBB0_3134
	s_lshl_b32 s3, s2, 2
	v_mbcnt_lo_u32_b32 v130, vcc_lo, 0
	s_add_i32 s3, s20, s3
	v_mbcnt_hi_u32_b32 v130, vcc_hi, v130
	v_lshl_add_u32 v130, v130, 2, s3
	ds_write_b32 v130, v4
